# attention output reduction: cross-row levels as reduce-scatters with v_permlane16_swap / v_permlane32_swap (no LDS round trips), one dword store per lane
# speedup vs baseline: 1.0082x; 1.0019x over previous
; #define LAS __attribute__((address_space(3)))
; __device__ __forceinline__ float bf_lo(unsigned v) { return __uint_as_float(v << 16); }
; __device__ __forceinline__ float bf_hi(unsigned v) { return __uint_as_float(v & 0xffff0000u); }
; __device__ __forceinline__ int lane_id() { int l; asm volatile("v_mbcnt_lo_u32_b32 %0, -1, 0\n\tv_mbcnt_hi_u32_b32 %0, -1, %0\n\ts_nop 1" : "=v"(l)); return l; }
; __device__ __forceinline__ void attn_query8(const unsigned char* __restrict__ KV8, const bf16_t* __restrict__ Z, const int* __restrict__ SEL, bf16_t* __restrict__ YMIX, int t, LAS float* sbuf  ) {
;     const int lane = lane_id(), hd = lane >> 3;
;     const int nsel = (t + 1 < 256) ? (t + 1) : 256, nb = (nsel + 7) >> 3;
;     int iv[4];
; #pragma unroll
;     for (int jj = 0; jj < 4; ++jj) { const int e = lane + 64 * jj; iv[jj] = (e < nsel) ? SEL[(size_t)t * 256 + e] : 0; }
;     f32x2v qf[8];
;     { const u32x4* qp = (const u32x4*)(Z + (size_t)t * ZLD + OFF_Q + lane * 16); const u32x4 a = qp[0], b = qp[1];
;       qf[0] = (f32x2v){bf_lo(a.x), bf_hi(a.x)}; qf[1] = (f32x2v){bf_lo(a.y), bf_hi(a.y)}; qf[2] = (f32x2v){bf_lo(a.z), bf_hi(a.z)}; qf[3] = (f32x2v){bf_lo(a.w), bf_hi(a.w)};
;       qf[4] = (f32x2v){bf_lo(b.x), bf_hi(b.x)}; qf[5] = (f32x2v){bf_lo(b.y), bf_hi(b.y)}; qf[6] = (f32x2v){bf_lo(b.z), bf_hi(b.z)}; qf[7] = (f32x2v){bf_lo(b.w), bf_hi(b.w)}; }
;     const __amdgpu_buffer_rsrc_t rs = __builtin_amdgcn_make_buffer_rsrc((void*)KV8, 0, 0x7fffffff, 0x00020000);
;     const int lvo = lane * 16;
;     LAS float* srow = sbuf + hd * 256;
;     u32x4 A[8], B[8], C[8];
;     const int lb = nb - 1;
.LBB0_1247:
	v_readlane_b32 s4, v248, 4
	v_readlane_b32 s5, v248, 5
	s_andn2_b64 vcc, exec, s[4:5]
	s_waitcnt vmcnt(0) lgkmcnt(0)
	s_barrier
	s_cbranch_vccnz .LBB0_1377
	s_mul_i32 s0, s81, 0x800
	s_and_b32 s5, s2, 7
	s_lshr_b32 s8, s2, 3
	s_lshl_b32 s8, s8, 3
	s_add_i32 s80, s8, s81
	s_lshl_b32 s8, s5, 22
	s_add_u32 s16, s60, 0x1b800000
	s_addc_u32 s17, s61, 0
	s_add_u32 s16, s16, s8
	s_addc_u32 s17, s17, 0
	s_and_b32 s17, s17, 0xffff
	s_mov_b32 s18, 0x400000
	s_mov_b32 s19, 0x20000
	s_mov_b32 s26, 0
	s_movk_i32 s27, 0x80
	s_mov_b32 s28, 0x3fb8aa3b
	v_and_b32_e32 v132, 7, v144
	v_lshlrev_b32_e32 v138, 4, v132
	v_lshrrev_b32_e32 v145, 3, v144
	v_lshl_add_u32 v139, v145, 7, s0
	v_lshl_add_u32 v148, v132, 7, s0
	v_lshl_add_u32 v148, v145, 2, v148
	v_xor_b32_e32 v140, 16, v144
	v_lshlrev_b32_e32 v140, 2, v140
	v_xor_b32_e32 v141, 32, v144
	v_lshlrev_b32_e32 v141, 2, v141
	v_mov_b32_e32 v142, 0xff800000
	v_lshlrev_b32_e32 v147, 2, v144
	s_lshl_b32 s8, s5, 8
	v_lshl_add_u32 v146, v132, 5, s8
	v_bfe_u32 v238, v144, 3, 1
	v_lshl_add_u32 v238, v238, 4, v146
	v_bfe_u32 v133, v144, 4, 1
	v_lshl_add_u32 v238, v133, 3, v238
	v_lshrrev_b32_e32 v133, 5, v144
	v_lshl_add_u32 v238, v133, 2, v238
	s_min_i32 s8, s80, 0xff
	s_add_i32 s8, s8, 1
	s_lshl_b32 s10, s80, 10
	s_add_u32 s10, s1, s10
	s_addc_u32 s11, s73, 0
	s_cmpk_eq_i32 s8, 0x100
	s_cbranch_scc1 .Latt_full_1
	v_mov_b32_e32 v240, 0
	v_add_u32_e32 v133, 0, v144
	v_cmp_gt_i32_e32 vcc, s8, v133
	s_and_saveexec_b64 s[12:13], vcc
	global_load_dword v240, v147, s[10:11] offset:0
	s_mov_b64 exec, s[12:13]
	v_mov_b32_e32 v241, 0
	v_add_u32_e32 v133, 64, v144
	v_cmp_gt_i32_e32 vcc, s8, v133
	s_and_saveexec_b64 s[12:13], vcc
	global_load_dword v241, v147, s[10:11] offset:256
	s_mov_b64 exec, s[12:13]
	v_mov_b32_e32 v242, 0
	v_add_u32_e32 v133, 128, v144
	v_cmp_gt_i32_e32 vcc, s8, v133
	s_and_saveexec_b64 s[12:13], vcc
	global_load_dword v242, v147, s[10:11] offset:512
	s_mov_b64 exec, s[12:13]
	v_mov_b32_e32 v243, 0
	v_add_u32_e32 v133, 192, v144
	v_cmp_gt_i32_e32 vcc, s8, v133
	s_and_saveexec_b64 s[12:13], vcc
	global_load_dword v243, v147, s[10:11] offset:768
	s_mov_b64 exec, s[12:13]
	s_branch .Latt_idx_1

; #define LAS __attribute__((address_space(3)))
; #define LDS_WAIT() asm volatile("s_waitcnt lgkmcnt(0)" ::: "memory")
; __device__ __forceinline__ void kv8_pv(const u32x4 (&buf)[8], f32x2v (&o2)[8], const LAS float* srow, int b) {
;     const LAS f32x4* p4 = (const LAS f32x4*)(srow + b * 8);
;     const f32x4 p0 = p4[0], p1 = p4[1];
;     const float p[8] = {p0.x, p0.y, p0.z, p0.w, p1.x, p1.y, p1.z, p1.w};
; #pragma unroll
;     for (int u = 0; u < 8; ++u) {
;         const u32x4 v = buf[u]; const f32x2v pp = {p[u], p[u]};
;         o2[0] = __builtin_elementwise_fma(pp, __builtin_amdgcn_cvt_pk_f32_fp8(v.x, false), o2[0]); o2[1] = __builtin_elementwise_fma(pp, __builtin_amdgcn_cvt_pk_f32_fp8(v.x, true), o2[1]);
;         o2[2] = __builtin_elementwise_fma(pp, __builtin_amdgcn_cvt_pk_f32_fp8(v.y, false), o2[2]); o2[3] = __builtin_elementwise_fma(pp, __builtin_amdgcn_cvt_pk_f32_fp8(v.y, true), o2[3]);
;         o2[4] = __builtin_elementwise_fma(pp, __builtin_amdgcn_cvt_pk_f32_fp8(v.z, false), o2[4]); o2[5] = __builtin_elementwise_fma(pp, __builtin_amdgcn_cvt_pk_f32_fp8(v.z, true), o2[5]);
;         o2[6] = __builtin_elementwise_fma(pp, __builtin_amdgcn_cvt_pk_f32_fp8(v.w, false), o2[6]); o2[7] = __builtin_elementwise_fma(pp, __builtin_amdgcn_cvt_pk_f32_fp8(v.w, true), o2[7]);
;     }
; __device__ __forceinline__ void attn_query8(const unsigned char* __restrict__ KV8, const bf16_t* __restrict__ Z, const int* __restrict__ SEL, bf16_t* __restrict__ YMIX, int t, LAS float* sbuf  ) {
;     ...
;     for (int h = 0; h < 8; ++h) {
;         float sv[4]; float mx = -__builtin_inff();
; #pragma unroll
;         for (int jj = 0; jj < 4; ++jj) { const int j = lane + 64 * jj; const float s = sbuf[h * 256 + j]; sv[jj] = (j < nsel) ? s : -__builtin_inff(); mx = fmaxf(mx, sv[jj]); }
;         mx = wave_max(mx); float sm = 0.f;
; #pragma unroll
;         for (int jj = 0; jj < 4; ++jj) { const int j = lane + 64 * jj; sv[jj] = (j < nsel) ? __expf(sv[jj] - mx) : 0.f; sm += sv[jj]; }
;         sm = wave_sum(sm); const float inv = 1.f / sm;
; #pragma unroll
;         for (int jj = 0; jj < 4; ++jj) sbuf[h * 256 + lane + 64 * jj] = sv[jj] * inv;
;     }
;     LDS_WAIT();
.Latt_nomask:
	v_max3_f32 v134, v150, v151, v152
	v_max3_f32 v134, v134, v153, v154
	v_max3_f32 v134, v134, v155, v156
	v_max3_f32 v134, v134, v157, v158
	v_max3_f32 v134, v134, v159, v160
	v_max3_f32 v134, v134, v161, v162
	v_max3_f32 v134, v134, v163, v164
	v_max3_f32 v134, v134, v165, v166
	v_max3_f32 v134, v134, v167, v168
	v_max3_f32 v134, v134, v169, v170
	v_max3_f32 v134, v134, v171, v172
	v_max3_f32 v134, v134, v173, v174
	v_max3_f32 v134, v134, v175, v176
	v_max3_f32 v134, v134, v177, v178
	v_max3_f32 v134, v134, v179, v180
	v_max_f32_e32 v134, v134, v181
	s_nop 1
	v_mov_b32_dpp v135, v134 row_ror:8 row_mask:0xf bank_mask:0xf
	s_nop 0
	v_max_f32_e32 v134, v134, v135
	ds_bpermute_b32 v135, v140, v134
	s_waitcnt lgkmcnt(0)
	v_max_f32_e32 v134, v134, v135
	ds_bpermute_b32 v135, v141, v134
	s_waitcnt lgkmcnt(0)
	v_max_f32_e32 v134, v134, v135
	v_mul_f32_e32 v134, 0xbfb8aa3b, v134
	v_fma_f32 v150, v150, s28, v134
	v_fma_f32 v151, v151, s28, v134
	v_fma_f32 v152, v152, s28, v134
	v_fma_f32 v153, v153, s28, v134
	v_fma_f32 v154, v154, s28, v134
	v_fma_f32 v155, v155, s28, v134
	v_fma_f32 v156, v156, s28, v134
	v_fma_f32 v157, v157, s28, v134
	v_fma_f32 v158, v158, s28, v134
	v_fma_f32 v159, v159, s28, v134
	v_fma_f32 v160, v160, s28, v134
	v_fma_f32 v161, v161, s28, v134
	v_fma_f32 v162, v162, s28, v134
	v_fma_f32 v163, v163, s28, v134
	v_fma_f32 v164, v164, s28, v134
	v_fma_f32 v165, v165, s28, v134
	v_fma_f32 v166, v166, s28, v134
	v_fma_f32 v167, v167, s28, v134
	v_fma_f32 v168, v168, s28, v134
	v_fma_f32 v169, v169, s28, v134
	v_fma_f32 v170, v170, s28, v134
	v_fma_f32 v171, v171, s28, v134
	v_fma_f32 v172, v172, s28, v134
	v_fma_f32 v173, v173, s28, v134
	v_fma_f32 v174, v174, s28, v134
	v_fma_f32 v175, v175, s28, v134
	v_fma_f32 v176, v176, s28, v134
	v_fma_f32 v177, v177, s28, v134
	v_fma_f32 v178, v178, s28, v134
	v_fma_f32 v179, v179, s28, v134
	v_fma_f32 v180, v180, s28, v134
	v_fma_f32 v181, v181, s28, v134
	v_exp_f32_e32 v150, v150
	v_exp_f32_e32 v151, v151
	v_exp_f32_e32 v152, v152
	v_exp_f32_e32 v153, v153
	v_exp_f32_e32 v154, v154
	v_exp_f32_e32 v155, v155
	v_exp_f32_e32 v156, v156
	v_exp_f32_e32 v157, v157
	v_exp_f32_e32 v158, v158
	v_exp_f32_e32 v159, v159
	v_exp_f32_e32 v160, v160
	v_exp_f32_e32 v161, v161
	v_exp_f32_e32 v162, v162
	v_exp_f32_e32 v163, v163
	v_exp_f32_e32 v164, v164
	v_exp_f32_e32 v165, v165
	v_exp_f32_e32 v166, v166
	v_exp_f32_e32 v167, v167
	v_exp_f32_e32 v168, v168
	v_exp_f32_e32 v169, v169
	v_exp_f32_e32 v170, v170
	v_exp_f32_e32 v171, v171
	v_exp_f32_e32 v172, v172
	v_exp_f32_e32 v173, v173
	v_exp_f32_e32 v174, v174
	v_exp_f32_e32 v175, v175
	v_exp_f32_e32 v176, v176
	v_exp_f32_e32 v177, v177
	v_exp_f32_e32 v178, v178
	v_exp_f32_e32 v179, v179
	v_exp_f32_e32 v180, v180
	v_exp_f32_e32 v181, v181
	s_nop 0
	v_add_f32_e32 v134, v150, v151
	v_add_f32_e32 v134, v134, v152
	v_add_f32_e32 v134, v134, v153
	v_add_f32_e32 v134, v134, v154
	v_add_f32_e32 v134, v134, v155
	v_add_f32_e32 v134, v134, v156
	v_add_f32_e32 v134, v134, v157
	v_add_f32_e32 v134, v134, v158
	v_add_f32_e32 v134, v134, v159
	v_add_f32_e32 v134, v134, v160
	v_add_f32_e32 v134, v134, v161
	v_add_f32_e32 v134, v134, v162
	v_add_f32_e32 v134, v134, v163
	v_add_f32_e32 v134, v134, v164
	v_add_f32_e32 v134, v134, v165
	v_add_f32_e32 v134, v134, v166
	v_add_f32_e32 v134, v134, v167
	v_add_f32_e32 v134, v134, v168
	v_add_f32_e32 v134, v134, v169
	v_add_f32_e32 v134, v134, v170
	v_add_f32_e32 v134, v134, v171
	v_add_f32_e32 v134, v134, v172
	v_add_f32_e32 v134, v134, v173
	v_add_f32_e32 v134, v134, v174
	v_add_f32_e32 v134, v134, v175
	v_add_f32_e32 v134, v134, v176
	v_add_f32_e32 v134, v134, v177
	v_add_f32_e32 v134, v134, v178
	v_add_f32_e32 v134, v134, v179
	v_add_f32_e32 v134, v134, v180
	v_add_f32_e32 v134, v134, v181
	s_nop 1
	v_mov_b32_dpp v135, v134 row_ror:8 row_mask:0xf bank_mask:0xf
	s_nop 0
	v_add_f32_e32 v134, v134, v135
	ds_bpermute_b32 v135, v140, v134
	s_waitcnt lgkmcnt(0)
	v_add_f32_e32 v134, v134, v135
	ds_bpermute_b32 v135, v141, v134
	s_waitcnt lgkmcnt(0)
	v_add_f32_e32 v134, v134, v135
	v_div_scale_f32 v132, s[8:9], v134, v134, 1.0
	v_rcp_f32_e32 v135, v132
	v_div_scale_f32 v133, vcc, 1.0, v134, 1.0
	v_fma_f32 v136, -v132, v135, 1.0
	v_fmac_f32_e32 v135, v136, v135
	v_mul_f32_e32 v136, v133, v135
	v_fma_f32 v137, -v132, v136, v133
	v_fmac_f32_e32 v136, v137, v135
	v_fma_f32 v132, -v132, v136, v133
	s_nop 1
	v_div_fmas_f32 v132, v132, v135, v136
	v_div_fixup_f32 v134, v132, v134, 1.0
	v_mov_b32_e32 v149, v134
	s_waitcnt vmcnt(31)
	ds_write_b32 v148, v240 offset:0
	ds_write_b32 v148, v241 offset:32
	ds_write_b32 v148, v242 offset:64
	ds_write_b32 v148, v243 offset:96
	v_cvt_pk_f32_fp8_e32 v[214:215], v0
	v_cvt_pk_f32_fp8_sdwa v[216:217], v0 src0_sel:WORD_1
	v_pk_mul_f32 v[198:199], v[150:151], v[214:215] op_sel_hi:[0,1]
	v_pk_mul_f32 v[200:201], v[150:151], v[216:217] op_sel_hi:[0,1]
	v_cvt_pk_f32_fp8_e32 v[218:219], v1
	v_cvt_pk_f32_fp8_sdwa v[220:221], v1 src0_sel:WORD_1
	v_pk_mul_f32 v[202:203], v[150:151], v[218:219] op_sel_hi:[0,1]
	v_pk_mul_f32 v[204:205], v[150:151], v[220:221] op_sel_hi:[0,1]
	v_cvt_pk_f32_fp8_e32 v[214:215], v2
	v_cvt_pk_f32_fp8_sdwa v[216:217], v2 src0_sel:WORD_1
	v_pk_mul_f32 v[206:207], v[150:151], v[214:215] op_sel_hi:[0,1]
	v_pk_mul_f32 v[208:209], v[150:151], v[216:217] op_sel_hi:[0,1]
	v_cvt_pk_f32_fp8_e32 v[218:219], v3
	v_cvt_pk_f32_fp8_sdwa v[220:221], v3 src0_sel:WORD_1
	v_pk_mul_f32 v[210:211], v[150:151], v[218:219] op_sel_hi:[0,1]
	v_pk_mul_f32 v[212:213], v[150:151], v[220:221] op_sel_hi:[0,1]
	s_waitcnt vmcnt(30)
; #define LAS __attribute__((address_space(3)))
; __device__ __forceinline__ void kv8_issue(u32x4 (&buf)[8], __amdgpu_buffer_rsrc_t rs, int voff  , int sbase  , const int (&iv)[4], int b) {
;     const int jj = b >> 3, l0 = (b & 7) * 8;
;     const int ivb = (jj == 0) ? iv[0] : (jj == 1) ? iv[1] : (jj == 2) ? iv[2] : iv[3];
; #pragma unroll
;     for (int u = 0; u < 8; ++u) { const int si = __builtin_amdgcn_readlane(ivb, l0 + u); buf[u] = __builtin_amdgcn_raw_buffer_load_b128(rs, voff, si * 2048 + sbase, KV8_AUX); }
; }
; __device__ __forceinline__ void kv8_pv(const u32x4 (&buf)[8], f32x2v (&o2)[8], const LAS float* srow, int b) {
;     const LAS f32x4* p4 = (const LAS f32x4*)(srow + b * 8);
;     const f32x4 p0 = p4[0], p1 = p4[1];
;     const float p[8] = {p0.x, p0.y, p0.z, p0.w, p1.x, p1.y, p1.z, p1.w};
; #pragma unroll
;     for (int u = 0; u < 8; ++u) {
;         const u32x4 v = buf[u]; const f32x2v pp = {p[u], p[u]};
;         o2[0] = __builtin_elementwise_fma(pp, __builtin_amdgcn_cvt_pk_f32_fp8(v.x, false), o2[0]); o2[1] = __builtin_elementwise_fma(pp, __builtin_amdgcn_cvt_pk_f32_fp8(v.x, true), o2[1]);
;         o2[2] = __builtin_elementwise_fma(pp, __builtin_amdgcn_cvt_pk_f32_fp8(v.y, false), o2[2]); o2[3] = __builtin_elementwise_fma(pp, __builtin_amdgcn_cvt_pk_f32_fp8(v.y, true), o2[3]);
;         o2[4] = __builtin_elementwise_fma(pp, __builtin_amdgcn_cvt_pk_f32_fp8(v.z, false), o2[4]); o2[5] = __builtin_elementwise_fma(pp, __builtin_amdgcn_cvt_pk_f32_fp8(v.z, true), o2[5]);
;         o2[6] = __builtin_elementwise_fma(pp, __builtin_amdgcn_cvt_pk_f32_fp8(v.w, false), o2[6]); o2[7] = __builtin_elementwise_fma(pp, __builtin_amdgcn_cvt_pk_f32_fp8(v.w, true), o2[7]);
;     }
	v_cvt_pk_f32_fp8_e32 v[214:215], v4
	v_cvt_pk_f32_fp8_sdwa v[216:217], v4 src0_sel:WORD_1
	v_pk_fma_f32 v[198:199], v[150:151], v[214:215], v[198:199] op_sel:[1,0,0]
	v_pk_fma_f32 v[200:201], v[150:151], v[216:217], v[200:201] op_sel:[1,0,0]
	v_cvt_pk_f32_fp8_e32 v[218:219], v5
	v_cvt_pk_f32_fp8_sdwa v[220:221], v5 src0_sel:WORD_1
	v_pk_fma_f32 v[202:203], v[150:151], v[218:219], v[202:203] op_sel:[1,0,0]
	v_pk_fma_f32 v[204:205], v[150:151], v[220:221], v[204:205] op_sel:[1,0,0]
	v_cvt_pk_f32_fp8_e32 v[214:215], v6
	v_cvt_pk_f32_fp8_sdwa v[216:217], v6 src0_sel:WORD_1
	v_pk_fma_f32 v[206:207], v[150:151], v[214:215], v[206:207] op_sel:[1,0,0]
	v_pk_fma_f32 v[208:209], v[150:151], v[216:217], v[208:209] op_sel:[1,0,0]
	v_cvt_pk_f32_fp8_e32 v[218:219], v7
	v_cvt_pk_f32_fp8_sdwa v[220:221], v7 src0_sel:WORD_1
	v_pk_fma_f32 v[210:211], v[150:151], v[218:219], v[210:211] op_sel:[1,0,0]
	v_pk_fma_f32 v[212:213], v[150:151], v[220:221], v[212:213] op_sel:[1,0,0]
	s_waitcnt vmcnt(29)
	v_cvt_pk_f32_fp8_e32 v[214:215], v8
	v_cvt_pk_f32_fp8_sdwa v[216:217], v8 src0_sel:WORD_1
	v_pk_fma_f32 v[198:199], v[152:153], v[214:215], v[198:199] op_sel_hi:[0,1,1]
	v_pk_fma_f32 v[200:201], v[152:153], v[216:217], v[200:201] op_sel_hi:[0,1,1]
	v_cvt_pk_f32_fp8_e32 v[218:219], v9
	v_cvt_pk_f32_fp8_sdwa v[220:221], v9 src0_sel:WORD_1
	v_pk_fma_f32 v[202:203], v[152:153], v[218:219], v[202:203] op_sel_hi:[0,1,1]
	v_pk_fma_f32 v[204:205], v[152:153], v[220:221], v[204:205] op_sel_hi:[0,1,1]
	v_cvt_pk_f32_fp8_e32 v[214:215], v10
	v_cvt_pk_f32_fp8_sdwa v[216:217], v10 src0_sel:WORD_1
	v_pk_fma_f32 v[206:207], v[152:153], v[214:215], v[206:207] op_sel_hi:[0,1,1]
	v_pk_fma_f32 v[208:209], v[152:153], v[216:217], v[208:209] op_sel_hi:[0,1,1]
	v_cvt_pk_f32_fp8_e32 v[218:219], v11
	v_cvt_pk_f32_fp8_sdwa v[220:221], v11 src0_sel:WORD_1
	v_pk_fma_f32 v[210:211], v[152:153], v[218:219], v[210:211] op_sel_hi:[0,1,1]
	v_pk_fma_f32 v[212:213], v[152:153], v[220:221], v[212:213] op_sel_hi:[0,1,1]
	s_waitcnt vmcnt(28)
	v_cvt_pk_f32_fp8_e32 v[214:215], v12
	v_cvt_pk_f32_fp8_sdwa v[216:217], v12 src0_sel:WORD_1
	v_pk_fma_f32 v[198:199], v[152:153], v[214:215], v[198:199] op_sel:[1,0,0]
	v_pk_fma_f32 v[200:201], v[152:153], v[216:217], v[200:201] op_sel:[1,0,0]
	v_cvt_pk_f32_fp8_e32 v[218:219], v13
	v_cvt_pk_f32_fp8_sdwa v[220:221], v13 src0_sel:WORD_1
	v_pk_fma_f32 v[202:203], v[152:153], v[218:219], v[202:203] op_sel:[1,0,0]
	v_pk_fma_f32 v[204:205], v[152:153], v[220:221], v[204:205] op_sel:[1,0,0]
	v_cvt_pk_f32_fp8_e32 v[214:215], v14
	v_cvt_pk_f32_fp8_sdwa v[216:217], v14 src0_sel:WORD_1
	v_pk_fma_f32 v[206:207], v[152:153], v[214:215], v[206:207] op_sel:[1,0,0]
	v_pk_fma_f32 v[208:209], v[152:153], v[216:217], v[208:209] op_sel:[1,0,0]
	v_cvt_pk_f32_fp8_e32 v[218:219], v15
	v_cvt_pk_f32_fp8_sdwa v[220:221], v15 src0_sel:WORD_1
	v_pk_fma_f32 v[210:211], v[152:153], v[218:219], v[210:211] op_sel:[1,0,0]
	v_pk_fma_f32 v[212:213], v[152:153], v[220:221], v[212:213] op_sel:[1,0,0]
	ds_read_b128 v[150:153], v139 offset:0
	s_waitcnt vmcnt(27)
	v_cvt_pk_f32_fp8_e32 v[214:215], v16
	v_cvt_pk_f32_fp8_sdwa v[216:217], v16 src0_sel:WORD_1
	v_pk_fma_f32 v[198:199], v[154:155], v[214:215], v[198:199] op_sel_hi:[0,1,1]
	v_pk_fma_f32 v[200:201], v[154:155], v[216:217], v[200:201] op_sel_hi:[0,1,1]
	v_cvt_pk_f32_fp8_e32 v[218:219], v17
	v_cvt_pk_f32_fp8_sdwa v[220:221], v17 src0_sel:WORD_1
	v_pk_fma_f32 v[202:203], v[154:155], v[218:219], v[202:203] op_sel_hi:[0,1,1]
	v_pk_fma_f32 v[204:205], v[154:155], v[220:221], v[204:205] op_sel_hi:[0,1,1]
	v_cvt_pk_f32_fp8_e32 v[214:215], v18
	v_cvt_pk_f32_fp8_sdwa v[216:217], v18 src0_sel:WORD_1
	v_pk_fma_f32 v[206:207], v[154:155], v[214:215], v[206:207] op_sel_hi:[0,1,1]
	v_pk_fma_f32 v[208:209], v[154:155], v[216:217], v[208:209] op_sel_hi:[0,1,1]
	v_cvt_pk_f32_fp8_e32 v[218:219], v19
	v_cvt_pk_f32_fp8_sdwa v[220:221], v19 src0_sel:WORD_1
	v_pk_fma_f32 v[210:211], v[154:155], v[218:219], v[210:211] op_sel_hi:[0,1,1]
	v_pk_fma_f32 v[212:213], v[154:155], v[220:221], v[212:213] op_sel_hi:[0,1,1]
	s_waitcnt vmcnt(26)
	v_cvt_pk_f32_fp8_e32 v[214:215], v20
	v_cvt_pk_f32_fp8_sdwa v[216:217], v20 src0_sel:WORD_1
	v_pk_fma_f32 v[198:199], v[154:155], v[214:215], v[198:199] op_sel:[1,0,0]
	v_pk_fma_f32 v[200:201], v[154:155], v[216:217], v[200:201] op_sel:[1,0,0]
	v_cvt_pk_f32_fp8_e32 v[218:219], v21
	v_cvt_pk_f32_fp8_sdwa v[220:221], v21 src0_sel:WORD_1
	v_pk_fma_f32 v[202:203], v[154:155], v[218:219], v[202:203] op_sel:[1,0,0]
	v_pk_fma_f32 v[204:205], v[154:155], v[220:221], v[204:205] op_sel:[1,0,0]
	v_cvt_pk_f32_fp8_e32 v[214:215], v22
	v_cvt_pk_f32_fp8_sdwa v[216:217], v22 src0_sel:WORD_1
	v_pk_fma_f32 v[206:207], v[154:155], v[214:215], v[206:207] op_sel:[1,0,0]
	v_pk_fma_f32 v[208:209], v[154:155], v[216:217], v[208:209] op_sel:[1,0,0]
	v_cvt_pk_f32_fp8_e32 v[218:219], v23
	v_cvt_pk_f32_fp8_sdwa v[220:221], v23 src0_sel:WORD_1
	v_pk_fma_f32 v[210:211], v[154:155], v[218:219], v[210:211] op_sel:[1,0,0]
	v_pk_fma_f32 v[212:213], v[154:155], v[220:221], v[212:213] op_sel:[1,0,0]
	s_waitcnt lgkmcnt(0)
	v_lshl_add_u32 v150, v150, 8, v138
	v_lshl_add_u32 v151, v151, 8, v138
	v_lshl_add_u32 v152, v152, 8, v138
	v_lshl_add_u32 v153, v153, 8, v138
	buffer_load_dwordx4 v[0:3], v150, s[16:19], s26 offen
	buffer_load_dwordx4 v[4:7], v151, s[16:19], s26 offen
	buffer_load_dwordx4 v[8:11], v152, s[16:19], s26 offen
	buffer_load_dwordx4 v[12:15], v153, s[16:19], s26 offen
	s_waitcnt vmcnt(29)
; #define LAS __attribute__((address_space(3)))
; __device__ __forceinline__ void kv8_issue(u32x4 (&buf)[8], __amdgpu_buffer_rsrc_t rs, int voff  , int sbase  , const int (&iv)[4], int b) {
;     const int jj = b >> 3, l0 = (b & 7) * 8;
;     const int ivb = (jj == 0) ? iv[0] : (jj == 1) ? iv[1] : (jj == 2) ? iv[2] : iv[3];
; #pragma unroll
;     for (int u = 0; u < 8; ++u) { const int si = __builtin_amdgcn_readlane(ivb, l0 + u); buf[u] = __builtin_amdgcn_raw_buffer_load_b128(rs, voff, si * 2048 + sbase, KV8_AUX); }
; }
; __device__ __forceinline__ void kv8_pv(const u32x4 (&buf)[8], f32x2v (&o2)[8], const LAS float* srow, int b) {
;     const LAS f32x4* p4 = (const LAS f32x4*)(srow + b * 8);
;     const f32x4 p0 = p4[0], p1 = p4[1];
;     const float p[8] = {p0.x, p0.y, p0.z, p0.w, p1.x, p1.y, p1.z, p1.w};
; #pragma unroll
;     for (int u = 0; u < 8; ++u) {
;         const u32x4 v = buf[u]; const f32x2v pp = {p[u], p[u]};
;         o2[0] = __builtin_elementwise_fma(pp, __builtin_amdgcn_cvt_pk_f32_fp8(v.x, false), o2[0]); o2[1] = __builtin_elementwise_fma(pp, __builtin_amdgcn_cvt_pk_f32_fp8(v.x, true), o2[1]);
;         o2[2] = __builtin_elementwise_fma(pp, __builtin_amdgcn_cvt_pk_f32_fp8(v.y, false), o2[2]); o2[3] = __builtin_elementwise_fma(pp, __builtin_amdgcn_cvt_pk_f32_fp8(v.y, true), o2[3]);
;         o2[4] = __builtin_elementwise_fma(pp, __builtin_amdgcn_cvt_pk_f32_fp8(v.z, false), o2[4]); o2[5] = __builtin_elementwise_fma(pp, __builtin_amdgcn_cvt_pk_f32_fp8(v.z, true), o2[5]);
;         o2[6] = __builtin_elementwise_fma(pp, __builtin_amdgcn_cvt_pk_f32_fp8(v.w, false), o2[6]); o2[7] = __builtin_elementwise_fma(pp, __builtin_amdgcn_cvt_pk_f32_fp8(v.w, true), o2[7]);
;     }
	v_cvt_pk_f32_fp8_e32 v[214:215], v24
	v_cvt_pk_f32_fp8_sdwa v[216:217], v24 src0_sel:WORD_1
	v_pk_fma_f32 v[198:199], v[156:157], v[214:215], v[198:199] op_sel_hi:[0,1,1]
	v_pk_fma_f32 v[200:201], v[156:157], v[216:217], v[200:201] op_sel_hi:[0,1,1]
	v_cvt_pk_f32_fp8_e32 v[218:219], v25
	v_cvt_pk_f32_fp8_sdwa v[220:221], v25 src0_sel:WORD_1
	v_pk_fma_f32 v[202:203], v[156:157], v[218:219], v[202:203] op_sel_hi:[0,1,1]
	v_pk_fma_f32 v[204:205], v[156:157], v[220:221], v[204:205] op_sel_hi:[0,1,1]
	v_cvt_pk_f32_fp8_e32 v[214:215], v26
	v_cvt_pk_f32_fp8_sdwa v[216:217], v26 src0_sel:WORD_1
	v_pk_fma_f32 v[206:207], v[156:157], v[214:215], v[206:207] op_sel_hi:[0,1,1]
	v_pk_fma_f32 v[208:209], v[156:157], v[216:217], v[208:209] op_sel_hi:[0,1,1]
	v_cvt_pk_f32_fp8_e32 v[218:219], v27
	v_cvt_pk_f32_fp8_sdwa v[220:221], v27 src0_sel:WORD_1
	v_pk_fma_f32 v[210:211], v[156:157], v[218:219], v[210:211] op_sel_hi:[0,1,1]
	v_pk_fma_f32 v[212:213], v[156:157], v[220:221], v[212:213] op_sel_hi:[0,1,1]
	s_waitcnt vmcnt(28)
	v_cvt_pk_f32_fp8_e32 v[214:215], v28
	v_cvt_pk_f32_fp8_sdwa v[216:217], v28 src0_sel:WORD_1
	v_pk_fma_f32 v[198:199], v[156:157], v[214:215], v[198:199] op_sel:[1,0,0]
	v_pk_fma_f32 v[200:201], v[156:157], v[216:217], v[200:201] op_sel:[1,0,0]
	v_cvt_pk_f32_fp8_e32 v[218:219], v29
	v_cvt_pk_f32_fp8_sdwa v[220:221], v29 src0_sel:WORD_1
	v_pk_fma_f32 v[202:203], v[156:157], v[218:219], v[202:203] op_sel:[1,0,0]
	v_pk_fma_f32 v[204:205], v[156:157], v[220:221], v[204:205] op_sel:[1,0,0]
	v_cvt_pk_f32_fp8_e32 v[214:215], v30
	v_cvt_pk_f32_fp8_sdwa v[216:217], v30 src0_sel:WORD_1
	v_pk_fma_f32 v[206:207], v[156:157], v[214:215], v[206:207] op_sel:[1,0,0]
	v_pk_fma_f32 v[208:209], v[156:157], v[216:217], v[208:209] op_sel:[1,0,0]
	v_cvt_pk_f32_fp8_e32 v[218:219], v31
	v_cvt_pk_f32_fp8_sdwa v[220:221], v31 src0_sel:WORD_1
	v_pk_fma_f32 v[210:211], v[156:157], v[218:219], v[210:211] op_sel:[1,0,0]
	v_pk_fma_f32 v[212:213], v[156:157], v[220:221], v[212:213] op_sel:[1,0,0]
	ds_read_b128 v[154:157], v139 offset:16
	s_waitcnt vmcnt(27)
	v_cvt_pk_f32_fp8_e32 v[214:215], v32
	v_cvt_pk_f32_fp8_sdwa v[216:217], v32 src0_sel:WORD_1
	v_pk_fma_f32 v[198:199], v[158:159], v[214:215], v[198:199] op_sel_hi:[0,1,1]
	v_pk_fma_f32 v[200:201], v[158:159], v[216:217], v[200:201] op_sel_hi:[0,1,1]
	v_cvt_pk_f32_fp8_e32 v[218:219], v33
	v_cvt_pk_f32_fp8_sdwa v[220:221], v33 src0_sel:WORD_1
	v_pk_fma_f32 v[202:203], v[158:159], v[218:219], v[202:203] op_sel_hi:[0,1,1]
	v_pk_fma_f32 v[204:205], v[158:159], v[220:221], v[204:205] op_sel_hi:[0,1,1]
	v_cvt_pk_f32_fp8_e32 v[214:215], v34
	v_cvt_pk_f32_fp8_sdwa v[216:217], v34 src0_sel:WORD_1
	v_pk_fma_f32 v[206:207], v[158:159], v[214:215], v[206:207] op_sel_hi:[0,1,1]
	v_pk_fma_f32 v[208:209], v[158:159], v[216:217], v[208:209] op_sel_hi:[0,1,1]
	v_cvt_pk_f32_fp8_e32 v[218:219], v35
	v_cvt_pk_f32_fp8_sdwa v[220:221], v35 src0_sel:WORD_1
	v_pk_fma_f32 v[210:211], v[158:159], v[218:219], v[210:211] op_sel_hi:[0,1,1]
	v_pk_fma_f32 v[212:213], v[158:159], v[220:221], v[212:213] op_sel_hi:[0,1,1]
	s_waitcnt vmcnt(26)
	v_cvt_pk_f32_fp8_e32 v[214:215], v36
	v_cvt_pk_f32_fp8_sdwa v[216:217], v36 src0_sel:WORD_1
	v_pk_fma_f32 v[198:199], v[158:159], v[214:215], v[198:199] op_sel:[1,0,0]
	v_pk_fma_f32 v[200:201], v[158:159], v[216:217], v[200:201] op_sel:[1,0,0]
	v_cvt_pk_f32_fp8_e32 v[218:219], v37
	v_cvt_pk_f32_fp8_sdwa v[220:221], v37 src0_sel:WORD_1
	v_pk_fma_f32 v[202:203], v[158:159], v[218:219], v[202:203] op_sel:[1,0,0]
	v_pk_fma_f32 v[204:205], v[158:159], v[220:221], v[204:205] op_sel:[1,0,0]
	v_cvt_pk_f32_fp8_e32 v[214:215], v38
	v_cvt_pk_f32_fp8_sdwa v[216:217], v38 src0_sel:WORD_1
	v_pk_fma_f32 v[206:207], v[158:159], v[214:215], v[206:207] op_sel:[1,0,0]
	v_pk_fma_f32 v[208:209], v[158:159], v[216:217], v[208:209] op_sel:[1,0,0]
	v_cvt_pk_f32_fp8_e32 v[218:219], v39
	v_cvt_pk_f32_fp8_sdwa v[220:221], v39 src0_sel:WORD_1
	v_pk_fma_f32 v[210:211], v[158:159], v[218:219], v[210:211] op_sel:[1,0,0]
	v_pk_fma_f32 v[212:213], v[158:159], v[220:221], v[212:213] op_sel:[1,0,0]
	s_waitcnt lgkmcnt(0)
	v_lshl_add_u32 v154, v154, 8, v138
	v_lshl_add_u32 v155, v155, 8, v138
	v_lshl_add_u32 v156, v156, 8, v138
	v_lshl_add_u32 v157, v157, 8, v138
	buffer_load_dwordx4 v[16:19], v154, s[16:19], s26 offen
	buffer_load_dwordx4 v[20:23], v155, s[16:19], s26 offen
	buffer_load_dwordx4 v[24:27], v156, s[16:19], s26 offen
	buffer_load_dwordx4 v[28:31], v157, s[16:19], s26 offen
	s_waitcnt vmcnt(29)
	v_cvt_pk_f32_fp8_e32 v[214:215], v40
	v_cvt_pk_f32_fp8_sdwa v[216:217], v40 src0_sel:WORD_1
	v_pk_fma_f32 v[198:199], v[160:161], v[214:215], v[198:199] op_sel_hi:[0,1,1]
	v_pk_fma_f32 v[200:201], v[160:161], v[216:217], v[200:201] op_sel_hi:[0,1,1]
	v_cvt_pk_f32_fp8_e32 v[218:219], v41
	v_cvt_pk_f32_fp8_sdwa v[220:221], v41 src0_sel:WORD_1
	v_pk_fma_f32 v[202:203], v[160:161], v[218:219], v[202:203] op_sel_hi:[0,1,1]
	v_pk_fma_f32 v[204:205], v[160:161], v[220:221], v[204:205] op_sel_hi:[0,1,1]
	v_cvt_pk_f32_fp8_e32 v[214:215], v42
	v_cvt_pk_f32_fp8_sdwa v[216:217], v42 src0_sel:WORD_1
	v_pk_fma_f32 v[206:207], v[160:161], v[214:215], v[206:207] op_sel_hi:[0,1,1]
	v_pk_fma_f32 v[208:209], v[160:161], v[216:217], v[208:209] op_sel_hi:[0,1,1]
	v_cvt_pk_f32_fp8_e32 v[218:219], v43
	v_cvt_pk_f32_fp8_sdwa v[220:221], v43 src0_sel:WORD_1
	v_pk_fma_f32 v[210:211], v[160:161], v[218:219], v[210:211] op_sel_hi:[0,1,1]
	v_pk_fma_f32 v[212:213], v[160:161], v[220:221], v[212:213] op_sel_hi:[0,1,1]
	s_waitcnt vmcnt(28)
; #define LAS __attribute__((address_space(3)))
; __device__ __forceinline__ void kv8_issue(u32x4 (&buf)[8], __amdgpu_buffer_rsrc_t rs, int voff  , int sbase  , const int (&iv)[4], int b) {
;     const int jj = b >> 3, l0 = (b & 7) * 8;
;     const int ivb = (jj == 0) ? iv[0] : (jj == 1) ? iv[1] : (jj == 2) ? iv[2] : iv[3];
; #pragma unroll
;     for (int u = 0; u < 8; ++u) { const int si = __builtin_amdgcn_readlane(ivb, l0 + u); buf[u] = __builtin_amdgcn_raw_buffer_load_b128(rs, voff, si * 2048 + sbase, KV8_AUX); }
; }
; __device__ __forceinline__ void kv8_pv(const u32x4 (&buf)[8], f32x2v (&o2)[8], const LAS float* srow, int b) {
;     const LAS f32x4* p4 = (const LAS f32x4*)(srow + b * 8);
;     const f32x4 p0 = p4[0], p1 = p4[1];
;     const float p[8] = {p0.x, p0.y, p0.z, p0.w, p1.x, p1.y, p1.z, p1.w};
; #pragma unroll
;     for (int u = 0; u < 8; ++u) {
;         const u32x4 v = buf[u]; const f32x2v pp = {p[u], p[u]};
;         o2[0] = __builtin_elementwise_fma(pp, __builtin_amdgcn_cvt_pk_f32_fp8(v.x, false), o2[0]); o2[1] = __builtin_elementwise_fma(pp, __builtin_amdgcn_cvt_pk_f32_fp8(v.x, true), o2[1]);
;         o2[2] = __builtin_elementwise_fma(pp, __builtin_amdgcn_cvt_pk_f32_fp8(v.y, false), o2[2]); o2[3] = __builtin_elementwise_fma(pp, __builtin_amdgcn_cvt_pk_f32_fp8(v.y, true), o2[3]);
;         o2[4] = __builtin_elementwise_fma(pp, __builtin_amdgcn_cvt_pk_f32_fp8(v.z, false), o2[4]); o2[5] = __builtin_elementwise_fma(pp, __builtin_amdgcn_cvt_pk_f32_fp8(v.z, true), o2[5]);
;         o2[6] = __builtin_elementwise_fma(pp, __builtin_amdgcn_cvt_pk_f32_fp8(v.w, false), o2[6]); o2[7] = __builtin_elementwise_fma(pp, __builtin_amdgcn_cvt_pk_f32_fp8(v.w, true), o2[7]);
;     }
	v_cvt_pk_f32_fp8_e32 v[214:215], v44
	v_cvt_pk_f32_fp8_sdwa v[216:217], v44 src0_sel:WORD_1
	v_pk_fma_f32 v[198:199], v[160:161], v[214:215], v[198:199] op_sel:[1,0,0]
	v_pk_fma_f32 v[200:201], v[160:161], v[216:217], v[200:201] op_sel:[1,0,0]
	v_cvt_pk_f32_fp8_e32 v[218:219], v45
	v_cvt_pk_f32_fp8_sdwa v[220:221], v45 src0_sel:WORD_1
	v_pk_fma_f32 v[202:203], v[160:161], v[218:219], v[202:203] op_sel:[1,0,0]
	v_pk_fma_f32 v[204:205], v[160:161], v[220:221], v[204:205] op_sel:[1,0,0]
	v_cvt_pk_f32_fp8_e32 v[214:215], v46
	v_cvt_pk_f32_fp8_sdwa v[216:217], v46 src0_sel:WORD_1
	v_pk_fma_f32 v[206:207], v[160:161], v[214:215], v[206:207] op_sel:[1,0,0]
	v_pk_fma_f32 v[208:209], v[160:161], v[216:217], v[208:209] op_sel:[1,0,0]
	v_cvt_pk_f32_fp8_e32 v[218:219], v47
	v_cvt_pk_f32_fp8_sdwa v[220:221], v47 src0_sel:WORD_1
	v_pk_fma_f32 v[210:211], v[160:161], v[218:219], v[210:211] op_sel:[1,0,0]
	v_pk_fma_f32 v[212:213], v[160:161], v[220:221], v[212:213] op_sel:[1,0,0]
	ds_read_b128 v[158:161], v139 offset:32
	s_waitcnt vmcnt(27)
	v_cvt_pk_f32_fp8_e32 v[214:215], v48
	v_cvt_pk_f32_fp8_sdwa v[216:217], v48 src0_sel:WORD_1
	v_pk_fma_f32 v[198:199], v[162:163], v[214:215], v[198:199] op_sel_hi:[0,1,1]
	v_pk_fma_f32 v[200:201], v[162:163], v[216:217], v[200:201] op_sel_hi:[0,1,1]
	v_cvt_pk_f32_fp8_e32 v[218:219], v49
	v_cvt_pk_f32_fp8_sdwa v[220:221], v49 src0_sel:WORD_1
	v_pk_fma_f32 v[202:203], v[162:163], v[218:219], v[202:203] op_sel_hi:[0,1,1]
	v_pk_fma_f32 v[204:205], v[162:163], v[220:221], v[204:205] op_sel_hi:[0,1,1]
	v_cvt_pk_f32_fp8_e32 v[214:215], v50
	v_cvt_pk_f32_fp8_sdwa v[216:217], v50 src0_sel:WORD_1
	v_pk_fma_f32 v[206:207], v[162:163], v[214:215], v[206:207] op_sel_hi:[0,1,1]
	v_pk_fma_f32 v[208:209], v[162:163], v[216:217], v[208:209] op_sel_hi:[0,1,1]
	v_cvt_pk_f32_fp8_e32 v[218:219], v51
	v_cvt_pk_f32_fp8_sdwa v[220:221], v51 src0_sel:WORD_1
	v_pk_fma_f32 v[210:211], v[162:163], v[218:219], v[210:211] op_sel_hi:[0,1,1]
	v_pk_fma_f32 v[212:213], v[162:163], v[220:221], v[212:213] op_sel_hi:[0,1,1]
	s_waitcnt vmcnt(26)
	v_cvt_pk_f32_fp8_e32 v[214:215], v52
	v_cvt_pk_f32_fp8_sdwa v[216:217], v52 src0_sel:WORD_1
	v_pk_fma_f32 v[198:199], v[162:163], v[214:215], v[198:199] op_sel:[1,0,0]
	v_pk_fma_f32 v[200:201], v[162:163], v[216:217], v[200:201] op_sel:[1,0,0]
	v_cvt_pk_f32_fp8_e32 v[218:219], v53
	v_cvt_pk_f32_fp8_sdwa v[220:221], v53 src0_sel:WORD_1
	v_pk_fma_f32 v[202:203], v[162:163], v[218:219], v[202:203] op_sel:[1,0,0]
	v_pk_fma_f32 v[204:205], v[162:163], v[220:221], v[204:205] op_sel:[1,0,0]
	v_cvt_pk_f32_fp8_e32 v[214:215], v54
	v_cvt_pk_f32_fp8_sdwa v[216:217], v54 src0_sel:WORD_1
	v_pk_fma_f32 v[206:207], v[162:163], v[214:215], v[206:207] op_sel:[1,0,0]
	v_pk_fma_f32 v[208:209], v[162:163], v[216:217], v[208:209] op_sel:[1,0,0]
	v_cvt_pk_f32_fp8_e32 v[218:219], v55
	v_cvt_pk_f32_fp8_sdwa v[220:221], v55 src0_sel:WORD_1
	v_pk_fma_f32 v[210:211], v[162:163], v[218:219], v[210:211] op_sel:[1,0,0]
	v_pk_fma_f32 v[212:213], v[162:163], v[220:221], v[212:213] op_sel:[1,0,0]
	s_waitcnt lgkmcnt(0)
	v_lshl_add_u32 v158, v158, 8, v138
	v_lshl_add_u32 v159, v159, 8, v138
	v_lshl_add_u32 v160, v160, 8, v138
	v_lshl_add_u32 v161, v161, 8, v138
	buffer_load_dwordx4 v[32:35], v158, s[16:19], s26 offen
	buffer_load_dwordx4 v[36:39], v159, s[16:19], s26 offen
	buffer_load_dwordx4 v[40:43], v160, s[16:19], s26 offen
	buffer_load_dwordx4 v[44:47], v161, s[16:19], s26 offen
	s_waitcnt vmcnt(29)
	v_cvt_pk_f32_fp8_e32 v[214:215], v56
	v_cvt_pk_f32_fp8_sdwa v[216:217], v56 src0_sel:WORD_1
	v_pk_fma_f32 v[198:199], v[164:165], v[214:215], v[198:199] op_sel_hi:[0,1,1]
	v_pk_fma_f32 v[200:201], v[164:165], v[216:217], v[200:201] op_sel_hi:[0,1,1]
	v_cvt_pk_f32_fp8_e32 v[218:219], v57
	v_cvt_pk_f32_fp8_sdwa v[220:221], v57 src0_sel:WORD_1
	v_pk_fma_f32 v[202:203], v[164:165], v[218:219], v[202:203] op_sel_hi:[0,1,1]
	v_pk_fma_f32 v[204:205], v[164:165], v[220:221], v[204:205] op_sel_hi:[0,1,1]
	v_cvt_pk_f32_fp8_e32 v[214:215], v58
	v_cvt_pk_f32_fp8_sdwa v[216:217], v58 src0_sel:WORD_1
	v_pk_fma_f32 v[206:207], v[164:165], v[214:215], v[206:207] op_sel_hi:[0,1,1]
	v_pk_fma_f32 v[208:209], v[164:165], v[216:217], v[208:209] op_sel_hi:[0,1,1]
	v_cvt_pk_f32_fp8_e32 v[218:219], v59
	v_cvt_pk_f32_fp8_sdwa v[220:221], v59 src0_sel:WORD_1
	v_pk_fma_f32 v[210:211], v[164:165], v[218:219], v[210:211] op_sel_hi:[0,1,1]
	v_pk_fma_f32 v[212:213], v[164:165], v[220:221], v[212:213] op_sel_hi:[0,1,1]
	s_waitcnt vmcnt(28)
	v_cvt_pk_f32_fp8_e32 v[214:215], v60
	v_cvt_pk_f32_fp8_sdwa v[216:217], v60 src0_sel:WORD_1
	v_pk_fma_f32 v[198:199], v[164:165], v[214:215], v[198:199] op_sel:[1,0,0]
	v_pk_fma_f32 v[200:201], v[164:165], v[216:217], v[200:201] op_sel:[1,0,0]
	v_cvt_pk_f32_fp8_e32 v[218:219], v61
	v_cvt_pk_f32_fp8_sdwa v[220:221], v61 src0_sel:WORD_1
	v_pk_fma_f32 v[202:203], v[164:165], v[218:219], v[202:203] op_sel:[1,0,0]
	v_pk_fma_f32 v[204:205], v[164:165], v[220:221], v[204:205] op_sel:[1,0,0]
	v_cvt_pk_f32_fp8_e32 v[214:215], v62
	v_cvt_pk_f32_fp8_sdwa v[216:217], v62 src0_sel:WORD_1
	v_pk_fma_f32 v[206:207], v[164:165], v[214:215], v[206:207] op_sel:[1,0,0]
	v_pk_fma_f32 v[208:209], v[164:165], v[216:217], v[208:209] op_sel:[1,0,0]
	v_cvt_pk_f32_fp8_e32 v[218:219], v63
	v_cvt_pk_f32_fp8_sdwa v[220:221], v63 src0_sel:WORD_1
	v_pk_fma_f32 v[210:211], v[164:165], v[218:219], v[210:211] op_sel:[1,0,0]
	v_pk_fma_f32 v[212:213], v[164:165], v[220:221], v[212:213] op_sel:[1,0,0]
	ds_read_b128 v[162:165], v139 offset:48
	s_waitcnt vmcnt(27)
; #define LAS __attribute__((address_space(3)))
; __device__ __forceinline__ void kv8_issue(u32x4 (&buf)[8], __amdgpu_buffer_rsrc_t rs, int voff  , int sbase  , const int (&iv)[4], int b) {
;     const int jj = b >> 3, l0 = (b & 7) * 8;
;     const int ivb = (jj == 0) ? iv[0] : (jj == 1) ? iv[1] : (jj == 2) ? iv[2] : iv[3];
; #pragma unroll
;     for (int u = 0; u < 8; ++u) { const int si = __builtin_amdgcn_readlane(ivb, l0 + u); buf[u] = __builtin_amdgcn_raw_buffer_load_b128(rs, voff, si * 2048 + sbase, KV8_AUX); }
; }
; __device__ __forceinline__ void kv8_pv(const u32x4 (&buf)[8], f32x2v (&o2)[8], const LAS float* srow, int b) {
;     const LAS f32x4* p4 = (const LAS f32x4*)(srow + b * 8);
;     const f32x4 p0 = p4[0], p1 = p4[1];
;     const float p[8] = {p0.x, p0.y, p0.z, p0.w, p1.x, p1.y, p1.z, p1.w};
; #pragma unroll
;     for (int u = 0; u < 8; ++u) {
;         const u32x4 v = buf[u]; const f32x2v pp = {p[u], p[u]};
;         o2[0] = __builtin_elementwise_fma(pp, __builtin_amdgcn_cvt_pk_f32_fp8(v.x, false), o2[0]); o2[1] = __builtin_elementwise_fma(pp, __builtin_amdgcn_cvt_pk_f32_fp8(v.x, true), o2[1]);
;         o2[2] = __builtin_elementwise_fma(pp, __builtin_amdgcn_cvt_pk_f32_fp8(v.y, false), o2[2]); o2[3] = __builtin_elementwise_fma(pp, __builtin_amdgcn_cvt_pk_f32_fp8(v.y, true), o2[3]);
;         o2[4] = __builtin_elementwise_fma(pp, __builtin_amdgcn_cvt_pk_f32_fp8(v.z, false), o2[4]); o2[5] = __builtin_elementwise_fma(pp, __builtin_amdgcn_cvt_pk_f32_fp8(v.z, true), o2[5]);
;         o2[6] = __builtin_elementwise_fma(pp, __builtin_amdgcn_cvt_pk_f32_fp8(v.w, false), o2[6]); o2[7] = __builtin_elementwise_fma(pp, __builtin_amdgcn_cvt_pk_f32_fp8(v.w, true), o2[7]);
;     }
	v_cvt_pk_f32_fp8_e32 v[214:215], v64
	v_cvt_pk_f32_fp8_sdwa v[216:217], v64 src0_sel:WORD_1
	v_pk_fma_f32 v[198:199], v[166:167], v[214:215], v[198:199] op_sel_hi:[0,1,1]
	v_pk_fma_f32 v[200:201], v[166:167], v[216:217], v[200:201] op_sel_hi:[0,1,1]
	v_cvt_pk_f32_fp8_e32 v[218:219], v65
	v_cvt_pk_f32_fp8_sdwa v[220:221], v65 src0_sel:WORD_1
	v_pk_fma_f32 v[202:203], v[166:167], v[218:219], v[202:203] op_sel_hi:[0,1,1]
	v_pk_fma_f32 v[204:205], v[166:167], v[220:221], v[204:205] op_sel_hi:[0,1,1]
	v_cvt_pk_f32_fp8_e32 v[214:215], v66
	v_cvt_pk_f32_fp8_sdwa v[216:217], v66 src0_sel:WORD_1
	v_pk_fma_f32 v[206:207], v[166:167], v[214:215], v[206:207] op_sel_hi:[0,1,1]
	v_pk_fma_f32 v[208:209], v[166:167], v[216:217], v[208:209] op_sel_hi:[0,1,1]
	v_cvt_pk_f32_fp8_e32 v[218:219], v67
	v_cvt_pk_f32_fp8_sdwa v[220:221], v67 src0_sel:WORD_1
	v_pk_fma_f32 v[210:211], v[166:167], v[218:219], v[210:211] op_sel_hi:[0,1,1]
	v_pk_fma_f32 v[212:213], v[166:167], v[220:221], v[212:213] op_sel_hi:[0,1,1]
	s_waitcnt vmcnt(26)
	v_cvt_pk_f32_fp8_e32 v[214:215], v68
	v_cvt_pk_f32_fp8_sdwa v[216:217], v68 src0_sel:WORD_1
	v_pk_fma_f32 v[198:199], v[166:167], v[214:215], v[198:199] op_sel:[1,0,0]
	v_pk_fma_f32 v[200:201], v[166:167], v[216:217], v[200:201] op_sel:[1,0,0]
	v_cvt_pk_f32_fp8_e32 v[218:219], v69
	v_cvt_pk_f32_fp8_sdwa v[220:221], v69 src0_sel:WORD_1
	v_pk_fma_f32 v[202:203], v[166:167], v[218:219], v[202:203] op_sel:[1,0,0]
	v_pk_fma_f32 v[204:205], v[166:167], v[220:221], v[204:205] op_sel:[1,0,0]
	v_cvt_pk_f32_fp8_e32 v[214:215], v70
	v_cvt_pk_f32_fp8_sdwa v[216:217], v70 src0_sel:WORD_1
	v_pk_fma_f32 v[206:207], v[166:167], v[214:215], v[206:207] op_sel:[1,0,0]
	v_pk_fma_f32 v[208:209], v[166:167], v[216:217], v[208:209] op_sel:[1,0,0]
	v_cvt_pk_f32_fp8_e32 v[218:219], v71
	v_cvt_pk_f32_fp8_sdwa v[220:221], v71 src0_sel:WORD_1
	v_pk_fma_f32 v[210:211], v[166:167], v[218:219], v[210:211] op_sel:[1,0,0]
	v_pk_fma_f32 v[212:213], v[166:167], v[220:221], v[212:213] op_sel:[1,0,0]
	s_waitcnt lgkmcnt(0)
	v_lshl_add_u32 v162, v162, 8, v138
	v_lshl_add_u32 v163, v163, 8, v138
	v_lshl_add_u32 v164, v164, 8, v138
	v_lshl_add_u32 v165, v165, 8, v138
	buffer_load_dwordx4 v[48:51], v162, s[16:19], s26 offen
	buffer_load_dwordx4 v[52:55], v163, s[16:19], s26 offen
	buffer_load_dwordx4 v[56:59], v164, s[16:19], s26 offen
	buffer_load_dwordx4 v[60:63], v165, s[16:19], s26 offen
	s_waitcnt vmcnt(29)
	v_cvt_pk_f32_fp8_e32 v[214:215], v72
	v_cvt_pk_f32_fp8_sdwa v[216:217], v72 src0_sel:WORD_1
	v_pk_fma_f32 v[198:199], v[168:169], v[214:215], v[198:199] op_sel_hi:[0,1,1]
	v_pk_fma_f32 v[200:201], v[168:169], v[216:217], v[200:201] op_sel_hi:[0,1,1]
	v_cvt_pk_f32_fp8_e32 v[218:219], v73
	v_cvt_pk_f32_fp8_sdwa v[220:221], v73 src0_sel:WORD_1
	v_pk_fma_f32 v[202:203], v[168:169], v[218:219], v[202:203] op_sel_hi:[0,1,1]
	v_pk_fma_f32 v[204:205], v[168:169], v[220:221], v[204:205] op_sel_hi:[0,1,1]
	v_cvt_pk_f32_fp8_e32 v[214:215], v74
	v_cvt_pk_f32_fp8_sdwa v[216:217], v74 src0_sel:WORD_1
	v_pk_fma_f32 v[206:207], v[168:169], v[214:215], v[206:207] op_sel_hi:[0,1,1]
	v_pk_fma_f32 v[208:209], v[168:169], v[216:217], v[208:209] op_sel_hi:[0,1,1]
	v_cvt_pk_f32_fp8_e32 v[218:219], v75
	v_cvt_pk_f32_fp8_sdwa v[220:221], v75 src0_sel:WORD_1
	v_pk_fma_f32 v[210:211], v[168:169], v[218:219], v[210:211] op_sel_hi:[0,1,1]
	v_pk_fma_f32 v[212:213], v[168:169], v[220:221], v[212:213] op_sel_hi:[0,1,1]
	s_waitcnt vmcnt(28)
	v_cvt_pk_f32_fp8_e32 v[214:215], v76
	v_cvt_pk_f32_fp8_sdwa v[216:217], v76 src0_sel:WORD_1
	v_pk_fma_f32 v[198:199], v[168:169], v[214:215], v[198:199] op_sel:[1,0,0]
	v_pk_fma_f32 v[200:201], v[168:169], v[216:217], v[200:201] op_sel:[1,0,0]
	v_cvt_pk_f32_fp8_e32 v[218:219], v77
	v_cvt_pk_f32_fp8_sdwa v[220:221], v77 src0_sel:WORD_1
	v_pk_fma_f32 v[202:203], v[168:169], v[218:219], v[202:203] op_sel:[1,0,0]
	v_pk_fma_f32 v[204:205], v[168:169], v[220:221], v[204:205] op_sel:[1,0,0]
	v_cvt_pk_f32_fp8_e32 v[214:215], v78
	v_cvt_pk_f32_fp8_sdwa v[216:217], v78 src0_sel:WORD_1
	v_pk_fma_f32 v[206:207], v[168:169], v[214:215], v[206:207] op_sel:[1,0,0]
	v_pk_fma_f32 v[208:209], v[168:169], v[216:217], v[208:209] op_sel:[1,0,0]
	v_cvt_pk_f32_fp8_e32 v[218:219], v79
	v_cvt_pk_f32_fp8_sdwa v[220:221], v79 src0_sel:WORD_1
	v_pk_fma_f32 v[210:211], v[168:169], v[218:219], v[210:211] op_sel:[1,0,0]
	v_pk_fma_f32 v[212:213], v[168:169], v[220:221], v[212:213] op_sel:[1,0,0]
	ds_read_b128 v[166:169], v139 offset:64
	s_waitcnt vmcnt(27)
	v_cvt_pk_f32_fp8_e32 v[214:215], v80
	v_cvt_pk_f32_fp8_sdwa v[216:217], v80 src0_sel:WORD_1
	v_pk_fma_f32 v[198:199], v[170:171], v[214:215], v[198:199] op_sel_hi:[0,1,1]
	v_pk_fma_f32 v[200:201], v[170:171], v[216:217], v[200:201] op_sel_hi:[0,1,1]
	v_cvt_pk_f32_fp8_e32 v[218:219], v81
	v_cvt_pk_f32_fp8_sdwa v[220:221], v81 src0_sel:WORD_1
	v_pk_fma_f32 v[202:203], v[170:171], v[218:219], v[202:203] op_sel_hi:[0,1,1]
	v_pk_fma_f32 v[204:205], v[170:171], v[220:221], v[204:205] op_sel_hi:[0,1,1]
	v_cvt_pk_f32_fp8_e32 v[214:215], v82
	v_cvt_pk_f32_fp8_sdwa v[216:217], v82 src0_sel:WORD_1
	v_pk_fma_f32 v[206:207], v[170:171], v[214:215], v[206:207] op_sel_hi:[0,1,1]
	v_pk_fma_f32 v[208:209], v[170:171], v[216:217], v[208:209] op_sel_hi:[0,1,1]
	v_cvt_pk_f32_fp8_e32 v[218:219], v83
	v_cvt_pk_f32_fp8_sdwa v[220:221], v83 src0_sel:WORD_1
	v_pk_fma_f32 v[210:211], v[170:171], v[218:219], v[210:211] op_sel_hi:[0,1,1]
	v_pk_fma_f32 v[212:213], v[170:171], v[220:221], v[212:213] op_sel_hi:[0,1,1]
	s_waitcnt vmcnt(26)
; #define LAS __attribute__((address_space(3)))
; __device__ __forceinline__ void kv8_issue(u32x4 (&buf)[8], __amdgpu_buffer_rsrc_t rs, int voff  , int sbase  , const int (&iv)[4], int b) {
;     const int jj = b >> 3, l0 = (b & 7) * 8;
;     const int ivb = (jj == 0) ? iv[0] : (jj == 1) ? iv[1] : (jj == 2) ? iv[2] : iv[3];
; #pragma unroll
;     for (int u = 0; u < 8; ++u) { const int si = __builtin_amdgcn_readlane(ivb, l0 + u); buf[u] = __builtin_amdgcn_raw_buffer_load_b128(rs, voff, si * 2048 + sbase, KV8_AUX); }
; }
; __device__ __forceinline__ void kv8_pv(const u32x4 (&buf)[8], f32x2v (&o2)[8], const LAS float* srow, int b) {
;     const LAS f32x4* p4 = (const LAS f32x4*)(srow + b * 8);
;     const f32x4 p0 = p4[0], p1 = p4[1];
;     const float p[8] = {p0.x, p0.y, p0.z, p0.w, p1.x, p1.y, p1.z, p1.w};
; #pragma unroll
;     for (int u = 0; u < 8; ++u) {
;         const u32x4 v = buf[u]; const f32x2v pp = {p[u], p[u]};
;         o2[0] = __builtin_elementwise_fma(pp, __builtin_amdgcn_cvt_pk_f32_fp8(v.x, false), o2[0]); o2[1] = __builtin_elementwise_fma(pp, __builtin_amdgcn_cvt_pk_f32_fp8(v.x, true), o2[1]);
;         o2[2] = __builtin_elementwise_fma(pp, __builtin_amdgcn_cvt_pk_f32_fp8(v.y, false), o2[2]); o2[3] = __builtin_elementwise_fma(pp, __builtin_amdgcn_cvt_pk_f32_fp8(v.y, true), o2[3]);
;         o2[4] = __builtin_elementwise_fma(pp, __builtin_amdgcn_cvt_pk_f32_fp8(v.z, false), o2[4]); o2[5] = __builtin_elementwise_fma(pp, __builtin_amdgcn_cvt_pk_f32_fp8(v.z, true), o2[5]);
;         o2[6] = __builtin_elementwise_fma(pp, __builtin_amdgcn_cvt_pk_f32_fp8(v.w, false), o2[6]); o2[7] = __builtin_elementwise_fma(pp, __builtin_amdgcn_cvt_pk_f32_fp8(v.w, true), o2[7]);
;     }
	v_cvt_pk_f32_fp8_e32 v[214:215], v84
	v_cvt_pk_f32_fp8_sdwa v[216:217], v84 src0_sel:WORD_1
	v_pk_fma_f32 v[198:199], v[170:171], v[214:215], v[198:199] op_sel:[1,0,0]
	v_pk_fma_f32 v[200:201], v[170:171], v[216:217], v[200:201] op_sel:[1,0,0]
	v_cvt_pk_f32_fp8_e32 v[218:219], v85
	v_cvt_pk_f32_fp8_sdwa v[220:221], v85 src0_sel:WORD_1
	v_pk_fma_f32 v[202:203], v[170:171], v[218:219], v[202:203] op_sel:[1,0,0]
	v_pk_fma_f32 v[204:205], v[170:171], v[220:221], v[204:205] op_sel:[1,0,0]
	v_cvt_pk_f32_fp8_e32 v[214:215], v86
	v_cvt_pk_f32_fp8_sdwa v[216:217], v86 src0_sel:WORD_1
	v_pk_fma_f32 v[206:207], v[170:171], v[214:215], v[206:207] op_sel:[1,0,0]
	v_pk_fma_f32 v[208:209], v[170:171], v[216:217], v[208:209] op_sel:[1,0,0]
	v_cvt_pk_f32_fp8_e32 v[218:219], v87
	v_cvt_pk_f32_fp8_sdwa v[220:221], v87 src0_sel:WORD_1
	v_pk_fma_f32 v[210:211], v[170:171], v[218:219], v[210:211] op_sel:[1,0,0]
	v_pk_fma_f32 v[212:213], v[170:171], v[220:221], v[212:213] op_sel:[1,0,0]
	s_waitcnt lgkmcnt(0)
	v_lshl_add_u32 v166, v166, 8, v138
	v_lshl_add_u32 v167, v167, 8, v138
	v_lshl_add_u32 v168, v168, 8, v138
	v_lshl_add_u32 v169, v169, 8, v138
	buffer_load_dwordx4 v[64:67], v166, s[16:19], s26 offen
	buffer_load_dwordx4 v[68:71], v167, s[16:19], s26 offen
	buffer_load_dwordx4 v[72:75], v168, s[16:19], s26 offen
	buffer_load_dwordx4 v[76:79], v169, s[16:19], s26 offen
	s_waitcnt vmcnt(29)
	v_cvt_pk_f32_fp8_e32 v[214:215], v88
	v_cvt_pk_f32_fp8_sdwa v[216:217], v88 src0_sel:WORD_1
	v_pk_fma_f32 v[198:199], v[172:173], v[214:215], v[198:199] op_sel_hi:[0,1,1]
	v_pk_fma_f32 v[200:201], v[172:173], v[216:217], v[200:201] op_sel_hi:[0,1,1]
	v_cvt_pk_f32_fp8_e32 v[218:219], v89
	v_cvt_pk_f32_fp8_sdwa v[220:221], v89 src0_sel:WORD_1
	v_pk_fma_f32 v[202:203], v[172:173], v[218:219], v[202:203] op_sel_hi:[0,1,1]
	v_pk_fma_f32 v[204:205], v[172:173], v[220:221], v[204:205] op_sel_hi:[0,1,1]
	v_cvt_pk_f32_fp8_e32 v[214:215], v90
	v_cvt_pk_f32_fp8_sdwa v[216:217], v90 src0_sel:WORD_1
	v_pk_fma_f32 v[206:207], v[172:173], v[214:215], v[206:207] op_sel_hi:[0,1,1]
	v_pk_fma_f32 v[208:209], v[172:173], v[216:217], v[208:209] op_sel_hi:[0,1,1]
	v_cvt_pk_f32_fp8_e32 v[218:219], v91
	v_cvt_pk_f32_fp8_sdwa v[220:221], v91 src0_sel:WORD_1
	v_pk_fma_f32 v[210:211], v[172:173], v[218:219], v[210:211] op_sel_hi:[0,1,1]
	v_pk_fma_f32 v[212:213], v[172:173], v[220:221], v[212:213] op_sel_hi:[0,1,1]
	s_waitcnt vmcnt(28)
	v_cvt_pk_f32_fp8_e32 v[214:215], v92
	v_cvt_pk_f32_fp8_sdwa v[216:217], v92 src0_sel:WORD_1
	v_pk_fma_f32 v[198:199], v[172:173], v[214:215], v[198:199] op_sel:[1,0,0]
	v_pk_fma_f32 v[200:201], v[172:173], v[216:217], v[200:201] op_sel:[1,0,0]
	v_cvt_pk_f32_fp8_e32 v[218:219], v93
	v_cvt_pk_f32_fp8_sdwa v[220:221], v93 src0_sel:WORD_1
	v_pk_fma_f32 v[202:203], v[172:173], v[218:219], v[202:203] op_sel:[1,0,0]
	v_pk_fma_f32 v[204:205], v[172:173], v[220:221], v[204:205] op_sel:[1,0,0]
	v_cvt_pk_f32_fp8_e32 v[214:215], v94
	v_cvt_pk_f32_fp8_sdwa v[216:217], v94 src0_sel:WORD_1
	v_pk_fma_f32 v[206:207], v[172:173], v[214:215], v[206:207] op_sel:[1,0,0]
	v_pk_fma_f32 v[208:209], v[172:173], v[216:217], v[208:209] op_sel:[1,0,0]
	v_cvt_pk_f32_fp8_e32 v[218:219], v95
	v_cvt_pk_f32_fp8_sdwa v[220:221], v95 src0_sel:WORD_1
	v_pk_fma_f32 v[210:211], v[172:173], v[218:219], v[210:211] op_sel:[1,0,0]
	v_pk_fma_f32 v[212:213], v[172:173], v[220:221], v[212:213] op_sel:[1,0,0]
	ds_read_b128 v[170:173], v139 offset:80
	s_waitcnt vmcnt(27)
	v_cvt_pk_f32_fp8_e32 v[214:215], v96
	v_cvt_pk_f32_fp8_sdwa v[216:217], v96 src0_sel:WORD_1
	v_pk_fma_f32 v[198:199], v[174:175], v[214:215], v[198:199] op_sel_hi:[0,1,1]
	v_pk_fma_f32 v[200:201], v[174:175], v[216:217], v[200:201] op_sel_hi:[0,1,1]
	v_cvt_pk_f32_fp8_e32 v[218:219], v97
	v_cvt_pk_f32_fp8_sdwa v[220:221], v97 src0_sel:WORD_1
	v_pk_fma_f32 v[202:203], v[174:175], v[218:219], v[202:203] op_sel_hi:[0,1,1]
	v_pk_fma_f32 v[204:205], v[174:175], v[220:221], v[204:205] op_sel_hi:[0,1,1]
	v_cvt_pk_f32_fp8_e32 v[214:215], v98
	v_cvt_pk_f32_fp8_sdwa v[216:217], v98 src0_sel:WORD_1
	v_pk_fma_f32 v[206:207], v[174:175], v[214:215], v[206:207] op_sel_hi:[0,1,1]
	v_pk_fma_f32 v[208:209], v[174:175], v[216:217], v[208:209] op_sel_hi:[0,1,1]
	v_cvt_pk_f32_fp8_e32 v[218:219], v99
	v_cvt_pk_f32_fp8_sdwa v[220:221], v99 src0_sel:WORD_1
	v_pk_fma_f32 v[210:211], v[174:175], v[218:219], v[210:211] op_sel_hi:[0,1,1]
	v_pk_fma_f32 v[212:213], v[174:175], v[220:221], v[212:213] op_sel_hi:[0,1,1]
	s_waitcnt vmcnt(26)
	v_cvt_pk_f32_fp8_e32 v[214:215], v100
	v_cvt_pk_f32_fp8_sdwa v[216:217], v100 src0_sel:WORD_1
	v_pk_fma_f32 v[198:199], v[174:175], v[214:215], v[198:199] op_sel:[1,0,0]
	v_pk_fma_f32 v[200:201], v[174:175], v[216:217], v[200:201] op_sel:[1,0,0]
	v_cvt_pk_f32_fp8_e32 v[218:219], v101
	v_cvt_pk_f32_fp8_sdwa v[220:221], v101 src0_sel:WORD_1
	v_pk_fma_f32 v[202:203], v[174:175], v[218:219], v[202:203] op_sel:[1,0,0]
	v_pk_fma_f32 v[204:205], v[174:175], v[220:221], v[204:205] op_sel:[1,0,0]
	v_cvt_pk_f32_fp8_e32 v[214:215], v102
	v_cvt_pk_f32_fp8_sdwa v[216:217], v102 src0_sel:WORD_1
	v_pk_fma_f32 v[206:207], v[174:175], v[214:215], v[206:207] op_sel:[1,0,0]
	v_pk_fma_f32 v[208:209], v[174:175], v[216:217], v[208:209] op_sel:[1,0,0]
	v_cvt_pk_f32_fp8_e32 v[218:219], v103
	v_cvt_pk_f32_fp8_sdwa v[220:221], v103 src0_sel:WORD_1
	v_pk_fma_f32 v[210:211], v[174:175], v[218:219], v[210:211] op_sel:[1,0,0]
	v_pk_fma_f32 v[212:213], v[174:175], v[220:221], v[212:213] op_sel:[1,0,0]
	s_waitcnt lgkmcnt(0)
; #define LAS __attribute__((address_space(3)))
; __device__ __forceinline__ void kv8_issue(u32x4 (&buf)[8], __amdgpu_buffer_rsrc_t rs, int voff  , int sbase  , const int (&iv)[4], int b) {
;     const int jj = b >> 3, l0 = (b & 7) * 8;
;     const int ivb = (jj == 0) ? iv[0] : (jj == 1) ? iv[1] : (jj == 2) ? iv[2] : iv[3];
; #pragma unroll
;     for (int u = 0; u < 8; ++u) { const int si = __builtin_amdgcn_readlane(ivb, l0 + u); buf[u] = __builtin_amdgcn_raw_buffer_load_b128(rs, voff, si * 2048 + sbase, KV8_AUX); }
; }
; __device__ __forceinline__ void kv8_pv(const u32x4 (&buf)[8], f32x2v (&o2)[8], const LAS float* srow, int b) {
;     const LAS f32x4* p4 = (const LAS f32x4*)(srow + b * 8);
;     const f32x4 p0 = p4[0], p1 = p4[1];
;     const float p[8] = {p0.x, p0.y, p0.z, p0.w, p1.x, p1.y, p1.z, p1.w};
; #pragma unroll
;     for (int u = 0; u < 8; ++u) {
;         const u32x4 v = buf[u]; const f32x2v pp = {p[u], p[u]};
;         o2[0] = __builtin_elementwise_fma(pp, __builtin_amdgcn_cvt_pk_f32_fp8(v.x, false), o2[0]); o2[1] = __builtin_elementwise_fma(pp, __builtin_amdgcn_cvt_pk_f32_fp8(v.x, true), o2[1]);
;         o2[2] = __builtin_elementwise_fma(pp, __builtin_amdgcn_cvt_pk_f32_fp8(v.y, false), o2[2]); o2[3] = __builtin_elementwise_fma(pp, __builtin_amdgcn_cvt_pk_f32_fp8(v.y, true), o2[3]);
;         o2[4] = __builtin_elementwise_fma(pp, __builtin_amdgcn_cvt_pk_f32_fp8(v.z, false), o2[4]); o2[5] = __builtin_elementwise_fma(pp, __builtin_amdgcn_cvt_pk_f32_fp8(v.z, true), o2[5]);
;         o2[6] = __builtin_elementwise_fma(pp, __builtin_amdgcn_cvt_pk_f32_fp8(v.w, false), o2[6]); o2[7] = __builtin_elementwise_fma(pp, __builtin_amdgcn_cvt_pk_f32_fp8(v.w, true), o2[7]);
;     }
	v_lshl_add_u32 v170, v170, 8, v138
	v_lshl_add_u32 v171, v171, 8, v138
	v_lshl_add_u32 v172, v172, 8, v138
	v_lshl_add_u32 v173, v173, 8, v138
	buffer_load_dwordx4 v[80:83], v170, s[16:19], s26 offen
	buffer_load_dwordx4 v[84:87], v171, s[16:19], s26 offen
	buffer_load_dwordx4 v[88:91], v172, s[16:19], s26 offen
	buffer_load_dwordx4 v[92:95], v173, s[16:19], s26 offen
	s_waitcnt vmcnt(29)
	v_cvt_pk_f32_fp8_e32 v[214:215], v104
	v_cvt_pk_f32_fp8_sdwa v[216:217], v104 src0_sel:WORD_1
	v_pk_fma_f32 v[198:199], v[176:177], v[214:215], v[198:199] op_sel_hi:[0,1,1]
	v_pk_fma_f32 v[200:201], v[176:177], v[216:217], v[200:201] op_sel_hi:[0,1,1]
	v_cvt_pk_f32_fp8_e32 v[218:219], v105
	v_cvt_pk_f32_fp8_sdwa v[220:221], v105 src0_sel:WORD_1
	v_pk_fma_f32 v[202:203], v[176:177], v[218:219], v[202:203] op_sel_hi:[0,1,1]
	v_pk_fma_f32 v[204:205], v[176:177], v[220:221], v[204:205] op_sel_hi:[0,1,1]
	v_cvt_pk_f32_fp8_e32 v[214:215], v106
	v_cvt_pk_f32_fp8_sdwa v[216:217], v106 src0_sel:WORD_1
	v_pk_fma_f32 v[206:207], v[176:177], v[214:215], v[206:207] op_sel_hi:[0,1,1]
	v_pk_fma_f32 v[208:209], v[176:177], v[216:217], v[208:209] op_sel_hi:[0,1,1]
	v_cvt_pk_f32_fp8_e32 v[218:219], v107
	v_cvt_pk_f32_fp8_sdwa v[220:221], v107 src0_sel:WORD_1
	v_pk_fma_f32 v[210:211], v[176:177], v[218:219], v[210:211] op_sel_hi:[0,1,1]
	v_pk_fma_f32 v[212:213], v[176:177], v[220:221], v[212:213] op_sel_hi:[0,1,1]
	s_waitcnt vmcnt(28)
	v_cvt_pk_f32_fp8_e32 v[214:215], v108
	v_cvt_pk_f32_fp8_sdwa v[216:217], v108 src0_sel:WORD_1
	v_pk_fma_f32 v[198:199], v[176:177], v[214:215], v[198:199] op_sel:[1,0,0]
	v_pk_fma_f32 v[200:201], v[176:177], v[216:217], v[200:201] op_sel:[1,0,0]
	v_cvt_pk_f32_fp8_e32 v[218:219], v109
	v_cvt_pk_f32_fp8_sdwa v[220:221], v109 src0_sel:WORD_1
	v_pk_fma_f32 v[202:203], v[176:177], v[218:219], v[202:203] op_sel:[1,0,0]
	v_pk_fma_f32 v[204:205], v[176:177], v[220:221], v[204:205] op_sel:[1,0,0]
	v_cvt_pk_f32_fp8_e32 v[214:215], v110
	v_cvt_pk_f32_fp8_sdwa v[216:217], v110 src0_sel:WORD_1
	v_pk_fma_f32 v[206:207], v[176:177], v[214:215], v[206:207] op_sel:[1,0,0]
	v_pk_fma_f32 v[208:209], v[176:177], v[216:217], v[208:209] op_sel:[1,0,0]
	v_cvt_pk_f32_fp8_e32 v[218:219], v111
	v_cvt_pk_f32_fp8_sdwa v[220:221], v111 src0_sel:WORD_1
	v_pk_fma_f32 v[210:211], v[176:177], v[218:219], v[210:211] op_sel:[1,0,0]
	v_pk_fma_f32 v[212:213], v[176:177], v[220:221], v[212:213] op_sel:[1,0,0]
	ds_read_b128 v[174:177], v139 offset:96
	s_waitcnt vmcnt(27)
	v_cvt_pk_f32_fp8_e32 v[214:215], v112
	v_cvt_pk_f32_fp8_sdwa v[216:217], v112 src0_sel:WORD_1
	v_pk_fma_f32 v[198:199], v[178:179], v[214:215], v[198:199] op_sel_hi:[0,1,1]
	v_pk_fma_f32 v[200:201], v[178:179], v[216:217], v[200:201] op_sel_hi:[0,1,1]
	v_cvt_pk_f32_fp8_e32 v[218:219], v113
	v_cvt_pk_f32_fp8_sdwa v[220:221], v113 src0_sel:WORD_1
	v_pk_fma_f32 v[202:203], v[178:179], v[218:219], v[202:203] op_sel_hi:[0,1,1]
	v_pk_fma_f32 v[204:205], v[178:179], v[220:221], v[204:205] op_sel_hi:[0,1,1]
	v_cvt_pk_f32_fp8_e32 v[214:215], v114
	v_cvt_pk_f32_fp8_sdwa v[216:217], v114 src0_sel:WORD_1
	v_pk_fma_f32 v[206:207], v[178:179], v[214:215], v[206:207] op_sel_hi:[0,1,1]
	v_pk_fma_f32 v[208:209], v[178:179], v[216:217], v[208:209] op_sel_hi:[0,1,1]
	v_cvt_pk_f32_fp8_e32 v[218:219], v115
	v_cvt_pk_f32_fp8_sdwa v[220:221], v115 src0_sel:WORD_1
	v_pk_fma_f32 v[210:211], v[178:179], v[218:219], v[210:211] op_sel_hi:[0,1,1]
	v_pk_fma_f32 v[212:213], v[178:179], v[220:221], v[212:213] op_sel_hi:[0,1,1]
	s_waitcnt vmcnt(26)
	v_cvt_pk_f32_fp8_e32 v[214:215], v116
	v_cvt_pk_f32_fp8_sdwa v[216:217], v116 src0_sel:WORD_1
	v_pk_fma_f32 v[198:199], v[178:179], v[214:215], v[198:199] op_sel:[1,0,0]
	v_pk_fma_f32 v[200:201], v[178:179], v[216:217], v[200:201] op_sel:[1,0,0]
	v_cvt_pk_f32_fp8_e32 v[218:219], v117
	v_cvt_pk_f32_fp8_sdwa v[220:221], v117 src0_sel:WORD_1
	v_pk_fma_f32 v[202:203], v[178:179], v[218:219], v[202:203] op_sel:[1,0,0]
	v_pk_fma_f32 v[204:205], v[178:179], v[220:221], v[204:205] op_sel:[1,0,0]
	v_cvt_pk_f32_fp8_e32 v[214:215], v118
	v_cvt_pk_f32_fp8_sdwa v[216:217], v118 src0_sel:WORD_1
	v_pk_fma_f32 v[206:207], v[178:179], v[214:215], v[206:207] op_sel:[1,0,0]
	v_pk_fma_f32 v[208:209], v[178:179], v[216:217], v[208:209] op_sel:[1,0,0]
	v_cvt_pk_f32_fp8_e32 v[218:219], v119
	v_cvt_pk_f32_fp8_sdwa v[220:221], v119 src0_sel:WORD_1
	v_pk_fma_f32 v[210:211], v[178:179], v[218:219], v[210:211] op_sel:[1,0,0]
	v_pk_fma_f32 v[212:213], v[178:179], v[220:221], v[212:213] op_sel:[1,0,0]
	s_waitcnt lgkmcnt(0)
	v_lshl_add_u32 v174, v174, 8, v138
	v_lshl_add_u32 v175, v175, 8, v138
	v_lshl_add_u32 v176, v176, 8, v138
	v_lshl_add_u32 v177, v177, 8, v138
	buffer_load_dwordx4 v[96:99], v174, s[16:19], s26 offen
	buffer_load_dwordx4 v[100:103], v175, s[16:19], s26 offen
	buffer_load_dwordx4 v[104:107], v176, s[16:19], s26 offen
	buffer_load_dwordx4 v[108:111], v177, s[16:19], s26 offen
	s_waitcnt vmcnt(29)
; __device__ __forceinline__ unsigned cvt_pk_bf16(float lo, float hi) { unsigned r; asm volatile("v_cvt_pk_bf16_f32 %0, %1, %2" : "=v"(r) : "v"(lo), "v"(hi)); return r; }
; #define LAS __attribute__((address_space(3)))
; __device__ __forceinline__ void kv8_pv(const u32x4 (&buf)[8], f32x2v (&o2)[8], const LAS float* srow, int b) {
;     const LAS f32x4* p4 = (const LAS f32x4*)(srow + b * 8);
;     const f32x4 p0 = p4[0], p1 = p4[1];
;     const float p[8] = {p0.x, p0.y, p0.z, p0.w, p1.x, p1.y, p1.z, p1.w};
; #pragma unroll
;     for (int u = 0; u < 8; ++u) {
;         const u32x4 v = buf[u]; const f32x2v pp = {p[u], p[u]};
;         o2[0] = __builtin_elementwise_fma(pp, __builtin_amdgcn_cvt_pk_f32_fp8(v.x, false), o2[0]); o2[1] = __builtin_elementwise_fma(pp, __builtin_amdgcn_cvt_pk_f32_fp8(v.x, true), o2[1]);
;         o2[2] = __builtin_elementwise_fma(pp, __builtin_amdgcn_cvt_pk_f32_fp8(v.y, false), o2[2]); o2[3] = __builtin_elementwise_fma(pp, __builtin_amdgcn_cvt_pk_f32_fp8(v.y, true), o2[3]);
;         o2[4] = __builtin_elementwise_fma(pp, __builtin_amdgcn_cvt_pk_f32_fp8(v.z, false), o2[4]); o2[5] = __builtin_elementwise_fma(pp, __builtin_amdgcn_cvt_pk_f32_fp8(v.z, true), o2[5]);
;         o2[6] = __builtin_elementwise_fma(pp, __builtin_amdgcn_cvt_pk_f32_fp8(v.w, false), o2[6]); o2[7] = __builtin_elementwise_fma(pp, __builtin_amdgcn_cvt_pk_f32_fp8(v.w, true), o2[7]);
;     }
; __device__ __forceinline__ void attn_query8(const unsigned char* __restrict__ KV8, const bf16_t* __restrict__ Z, const int* __restrict__ SEL, bf16_t* __restrict__ YMIX, int t, LAS float* sbuf  ) {
;     ...
;     u32x4 o0, o1;
;     o0.x = cvt_pk_bf16(o[0].x, o[0].y); o0.y = cvt_pk_bf16(o[1].x, o[1].y); o0.z = cvt_pk_bf16(o[2].x, o[2].y); o0.w = cvt_pk_bf16(o[3].x, o[3].y);
;     o1.x = cvt_pk_bf16(o[4].x, o[4].y); o1.y = cvt_pk_bf16(o[5].x, o[5].y); o1.z = cvt_pk_bf16(o[6].x, o[6].y); o1.w = cvt_pk_bf16(o[7].x, o[7].y);
;     u32x4* yp = (u32x4*)(YMIX + (size_t)t * D_ + 1024 + lane * 16);
;     yp[0] = o0; yp[1] = o1;
	v_cvt_pk_f32_fp8_e32 v[214:215], v120
	v_cvt_pk_f32_fp8_sdwa v[216:217], v120 src0_sel:WORD_1
	v_pk_fma_f32 v[198:199], v[180:181], v[214:215], v[198:199] op_sel_hi:[0,1,1]
	v_pk_fma_f32 v[200:201], v[180:181], v[216:217], v[200:201] op_sel_hi:[0,1,1]
	v_cvt_pk_f32_fp8_e32 v[218:219], v121
	v_cvt_pk_f32_fp8_sdwa v[220:221], v121 src0_sel:WORD_1
	v_pk_fma_f32 v[202:203], v[180:181], v[218:219], v[202:203] op_sel_hi:[0,1,1]
	v_pk_fma_f32 v[204:205], v[180:181], v[220:221], v[204:205] op_sel_hi:[0,1,1]
	v_cvt_pk_f32_fp8_e32 v[214:215], v122
	v_cvt_pk_f32_fp8_sdwa v[216:217], v122 src0_sel:WORD_1
	v_pk_fma_f32 v[206:207], v[180:181], v[214:215], v[206:207] op_sel_hi:[0,1,1]
	v_pk_fma_f32 v[208:209], v[180:181], v[216:217], v[208:209] op_sel_hi:[0,1,1]
	v_cvt_pk_f32_fp8_e32 v[218:219], v123
	v_cvt_pk_f32_fp8_sdwa v[220:221], v123 src0_sel:WORD_1
	v_pk_fma_f32 v[210:211], v[180:181], v[218:219], v[210:211] op_sel_hi:[0,1,1]
	v_pk_fma_f32 v[212:213], v[180:181], v[220:221], v[212:213] op_sel_hi:[0,1,1]
	s_waitcnt vmcnt(28)
	v_cvt_pk_f32_fp8_e32 v[214:215], v124
	v_cvt_pk_f32_fp8_sdwa v[216:217], v124 src0_sel:WORD_1
	v_pk_fma_f32 v[198:199], v[180:181], v[214:215], v[198:199] op_sel:[1,0,0]
	v_pk_fma_f32 v[200:201], v[180:181], v[216:217], v[200:201] op_sel:[1,0,0]
	v_cvt_pk_f32_fp8_e32 v[218:219], v125
	v_cvt_pk_f32_fp8_sdwa v[220:221], v125 src0_sel:WORD_1
	v_pk_fma_f32 v[202:203], v[180:181], v[218:219], v[202:203] op_sel:[1,0,0]
	v_pk_fma_f32 v[204:205], v[180:181], v[220:221], v[204:205] op_sel:[1,0,0]
	v_cvt_pk_f32_fp8_e32 v[214:215], v126
	v_cvt_pk_f32_fp8_sdwa v[216:217], v126 src0_sel:WORD_1
	v_pk_fma_f32 v[206:207], v[180:181], v[214:215], v[206:207] op_sel:[1,0,0]
	v_pk_fma_f32 v[208:209], v[180:181], v[216:217], v[208:209] op_sel:[1,0,0]
	v_cvt_pk_f32_fp8_e32 v[218:219], v127
	v_cvt_pk_f32_fp8_sdwa v[220:221], v127 src0_sel:WORD_1
	v_pk_fma_f32 v[210:211], v[180:181], v[218:219], v[210:211] op_sel:[1,0,0]
	v_pk_fma_f32 v[212:213], v[180:181], v[220:221], v[212:213] op_sel:[1,0,0]
	ds_read_b128 v[178:181], v139 offset:112
	v_add_f32_dpp v198, v198, v198 row_ror:8 row_mask:0xf bank_mask:0x3
	v_add_f32_dpp v199, v199, v199 row_ror:8 row_mask:0xf bank_mask:0x3
	v_add_f32_dpp v200, v200, v200 row_ror:8 row_mask:0xf bank_mask:0x3
	v_add_f32_dpp v201, v201, v201 row_ror:8 row_mask:0xf bank_mask:0x3
	v_add_f32_dpp v202, v202, v202 row_ror:8 row_mask:0xf bank_mask:0x3
	v_add_f32_dpp v203, v203, v203 row_ror:8 row_mask:0xf bank_mask:0x3
	v_add_f32_dpp v204, v204, v204 row_ror:8 row_mask:0xf bank_mask:0x3
	v_add_f32_dpp v205, v205, v205 row_ror:8 row_mask:0xf bank_mask:0x3
	v_add_f32_dpp v206, v206, v206 row_ror:8 row_mask:0xf bank_mask:0xc
	v_add_f32_dpp v207, v207, v207 row_ror:8 row_mask:0xf bank_mask:0xc
	v_add_f32_dpp v208, v208, v208 row_ror:8 row_mask:0xf bank_mask:0xc
	v_add_f32_dpp v209, v209, v209 row_ror:8 row_mask:0xf bank_mask:0xc
	v_add_f32_dpp v210, v210, v210 row_ror:8 row_mask:0xf bank_mask:0xc
	v_add_f32_dpp v211, v211, v211 row_ror:8 row_mask:0xf bank_mask:0xc
	v_add_f32_dpp v212, v212, v212 row_ror:8 row_mask:0xf bank_mask:0xc
	v_add_f32_dpp v213, v213, v213 row_ror:8 row_mask:0xf bank_mask:0xc
	v_mov_b32_dpp v198, v206 quad_perm:[0,1,2,3] row_mask:0xf bank_mask:0xc
	v_mov_b32_dpp v199, v207 quad_perm:[0,1,2,3] row_mask:0xf bank_mask:0xc
	v_mov_b32_dpp v200, v208 quad_perm:[0,1,2,3] row_mask:0xf bank_mask:0xc
	v_mov_b32_dpp v201, v209 quad_perm:[0,1,2,3] row_mask:0xf bank_mask:0xc
	v_mov_b32_dpp v202, v210 quad_perm:[0,1,2,3] row_mask:0xf bank_mask:0xc
	v_mov_b32_dpp v203, v211 quad_perm:[0,1,2,3] row_mask:0xf bank_mask:0xc
	v_mov_b32_dpp v204, v212 quad_perm:[0,1,2,3] row_mask:0xf bank_mask:0xc
	v_mov_b32_dpp v205, v213 quad_perm:[0,1,2,3] row_mask:0xf bank_mask:0xc
	s_waitcnt lgkmcnt(0)
	v_lshl_add_u32 v178, v178, 8, v138
	v_lshl_add_u32 v179, v179, 8, v138
	v_lshl_add_u32 v180, v180, 8, v138
	v_lshl_add_u32 v181, v181, 8, v138
	buffer_load_dwordx4 v[112:115], v178, s[16:19], s26 offen
	buffer_load_dwordx4 v[116:119], v179, s[16:19], s26 offen
	buffer_load_dwordx4 v[120:123], v180, s[16:19], s26 offen
	buffer_load_dwordx4 v[124:127], v181, s[16:19], s26 offen
	s_nop 1
	v_permlane16_swap_b32_e32 v198, v202
	v_add_f32_e32 v198, v198, v202
	v_permlane16_swap_b32_e32 v199, v203
	v_add_f32_e32 v199, v199, v203
	v_permlane16_swap_b32_e32 v200, v204
	v_add_f32_e32 v200, v200, v204
	v_permlane16_swap_b32_e32 v201, v205
	v_add_f32_e32 v201, v201, v205
	s_nop 0
	v_permlane32_swap_b32_e32 v198, v200
	v_add_f32_e32 v198, v198, v200
	v_permlane32_swap_b32_e32 v199, v201
	v_add_f32_e32 v199, v199, v201
	s_ashr_i32 s81, s80, 31
	s_lshl_b64 s[10:11], s[80:81], 12
	s_add_u32 s10, s14, s10
	s_addc_u32 s11, s15, s11
	v_mul_f32_e32 v198, v198, v149
	v_mul_f32_e32 v199, v199, v149
	v_cvt_pk_bf16_f32 v214, v198, v199
	global_store_dword v238, v214, s[10:11] offset:2048
	s_addk_i32 s80, 0x100
	s_cmpk_gt_i32 s80, 0x3fff
	s_cbranch_scc0 .Latt_unit
	s_waitcnt vmcnt(0)
